# speedup vs baseline: 1.0120x; 1.0040x over previous
; __device__ __forceinline__ unsigned pk2(float lo, float hi) { f32x2_t v = {lo, hi}; bf16x2_t b = __builtin_convertvector(v, bf16x2_t); return __builtin_bit_cast(unsigned, b); }
; __device__ __forceinline__ float bf_lo(unsigned w) { return __uint_as_float(w << 16); }
; __global__ void __launch_bounds__(512) fwd_megakernel(Args args) {
;     ...
;     if (PHMASK & 32) for (int m = gw; m < MTOK; m += NGW) {
;         const bf16_t* row = CQ + (size_t)m * 768;
;         {
;             u32x4 w = (u32x4){0u, 0u, 0u, 0u}; if (lane < 48) w = *(const u32x4*)(row + 8 * lane);
;             float v[8] = {bf_lo(w.x), bf_hi(w.x), bf_lo(w.y), bf_hi(w.y), bf_lo(w.z), bf_hi(w.z), bf_lo(w.w), bf_hi(w.w)}; float s = 0.f;
; #pragma unroll
;             for (int j = 0; j < 8; ++j) s += v[j] * v[j];
;             const float rr = __builtin_amdgcn_rsqf(wave_sum(s) * (1.0f / 384.0f) + EPS);
;             if (lane < 48) { const float* g = args.in[13] + 8 * lane; u32x4 o; o.x = pk2(v[0] * rr * g[0], v[1] * rr * g[1]); o.y = pk2(v[2] * rr * g[2], v[3] * rr * g[3]);
;                 o.z = pk2(v[4] * rr * g[4], v[5] * rr * g[5]); o.w = pk2(v[6] * rr * g[6], v[7] * rr * g[7]); *(u32x4*)(CQN + (size_t)m * 640 + 8 * lane) = o; }
;         }
;         {
;             u32x4 w = (u32x4){0u, 0u, 0u, 0u}; if (lane < 32) w = *(const u32x4*)(row + 384 + 8 * lane);
;             float v[8] = {bf_lo(w.x), bf_hi(w.x), bf_lo(w.y), bf_hi(w.y), bf_lo(w.z), bf_hi(w.z), bf_lo(w.w), bf_hi(w.w)}; float s = 0.f;
; #pragma unroll
;             for (int j = 0; j < 8; ++j) s += v[j] * v[j];
;             const float rr = __builtin_amdgcn_rsqf(wave_sum(s) * (1.0f / 256.0f) + EPS);
;             if (lane < 32) { const float* g = args.in[14] + 8 * lane; u32x4 o; o.x = pk2(v[0] * rr * g[0], v[1] * rr * g[1]); o.y = pk2(v[2] * rr * g[2], v[3] * rr * g[3]);
;                 o.z = pk2(v[4] * rr * g[4], v[5] * rr * g[5]); o.w = pk2(v[6] * rr * g[6], v[7] * rr * g[7]); *(u32x4*)(CQN + (size_t)m * 640 + 384 + 8 * lane) = o; }
;         }
;         {
;             const int i = lane & 31; const float v = __uint_as_float((unsigned)row[640 + i] << 16);
;             const float ssq = wave_sum(v * v) * 0.5f;
;             const float y = v * args.in[18][64 + i], pr = __shfl_xor(y, 16);
;             const int pos = tok_pos(m), fi = i & 15; const float c = ropeC_c[pos * 16 + fi], s = ropeC_s[pos * 16 + fi];
.LBB0_896:
	s_or_b64 exec, exec, s[4:5]
	s_cmp_gt_i32 s34, 0xbfff
	s_cbranch_scc1 .LBB0_911
	v_readlane_b32 s16, v247, 39
	v_readlane_b32 s24, v247, 47
	s_lshl_b64 s[14:15], s[34:35], 2
	v_lshlrev_b32_e32 v4, 5, v128
	v_mov_b32_e32 v5, 0
	v_readlane_b32 s17, v247, 40
	v_readlane_b32 s25, v247, 48
	s_add_u32 s24, s14, 0x3d00000
	v_lshl_add_u64 v[6:7], s[46:47], 0, v[4:5]
	v_lshl_add_u64 v[8:9], s[48:49], 0, v[4:5]
	v_lshlrev_b32_e32 v4, 2, v192
	s_addc_u32 s25, s15, 0
	s_lshl_b64 s[16:17], s[34:35], 7
	v_readlane_b32 s20, v247, 43
	v_readlane_b32 s21, v247, 44
	v_or_b32_e32 v0, s16, v4
	v_mov_b32_e32 v1, s17
	s_mov_b64 s[16:17], 0x3700000
	v_readlane_b32 s18, v247, 41
	v_readlane_b32 s19, v247, 42
	v_readlane_b32 s22, v247, 45
	v_readlane_b32 s23, v247, 46
	v_lshl_add_u64 v[10:11], s[20:21], 0, v[4:5]
	v_lshl_add_u64 v[12:13], v[0:1], 0, s[16:17]
	v_lshlrev_b32_e32 v4, 4, v128
	v_mov_b32_e32 v0, 0x500
	v_readlane_b32 s26, v247, 49
	v_readlane_b32 s27, v247, 50
	v_readlane_b32 s14, v247, 61
	v_mad_i64_i32 v[14:15], s[18:19], s34, v0, v[4:5]
	s_mul_hi_i32 s22, s34, 0x600
	s_mul_i32 s23, s34, 0x600
	v_mov_b32_e32 v0, 0x600
	v_readlane_b32 s30, v247, 53
	v_readlane_b32 s15, v247, 62
	s_mov_b32 s26, s14
	s_ashr_i32 s27, s14, 31
	v_mad_i64_i32 v[16:17], s[20:21], s34, v0, v[4:5]
	v_lshl_or_b32 v0, v192, 1, s23
	v_mov_b32_e32 v1, s22
	s_mov_b64 s[22:23], 0x15e00500
	v_cmp_gt_u32_e64 s[0:1], 48, v128
	v_cmp_gt_u32_e64 s[4:5], 32, v128
	v_cmp_gt_u32_e64 s[6:7], 16, v192
	v_cmp_eq_u32_e64 s[8:9], 0, v128
	s_lshl_b64 s[14:15], s[26:27], 2
	s_lshl_b64 s[16:17], s[26:27], 7
	s_mul_hi_i32 s19, s26, 0x500
	s_mul_i32 s18, s26, 0x500
	s_mul_hi_i32 s21, s26, 0x600
	s_mov_b32 s30, s26
	s_mul_i32 s20, s26, 0x600
	v_lshl_add_u64 v[18:19], v[0:1], 0, s[22:23]
	v_mov_b32_e32 v4, 0x358637bd
	s_movk_i32 s26, 0xfff
	v_lshlrev_b32_e32 v28, 2, v145
	v_readlane_b32 s28, v247, 51
	v_readlane_b32 s29, v247, 52
	v_readlane_b32 s31, v247, 54
	v_mov_b32_e32 v56, 0
	v_mov_b32_e32 v57, 0
	v_mov_b32_e32 v58, 0
	v_mov_b32_e32 v59, 0
	v_mov_b32_e32 v60, 0
	v_mov_b32_e32 v61, 0
	v_mov_b32_e32 v62, 0
	v_mov_b32_e32 v63, 0
	v_mov_b32_e32 v64, 0
	v_mov_b32_e32 v65, 0
	v_mov_b32_e32 v66, 0
	v_mov_b32_e32 v67, 0
	v_mov_b32_e32 v68, 0
	v_mov_b32_e32 v69, 0
	v_mov_b32_e32 v70, 0
	v_mov_b32_e32 v71, 0
	v_mov_b32_e32 v42, 0
	v_mov_b32_e32 v43, 0
	v_mov_b32_e32 v44, 0
	v_mov_b32_e32 v45, 0
	v_mov_b32_e32 v46, 0
	v_mov_b32_e32 v47, 0
	v_mov_b32_e32 v48, 0
	v_mov_b32_e32 v49, 0
	s_mov_b64 exec, s[0:1]
	global_load_dwordx4 v[56:59], v[6:7], off
	global_load_dwordx4 v[60:63], v[6:7], off offset:16
	s_mov_b64 exec, s[4:5]
	global_load_dwordx4 v[64:67], v[8:9], off
	global_load_dwordx4 v[68:71], v[8:9], off offset:16
	s_mov_b64 exec, -1
	global_load_dword v72, v[10:11], off offset:256
	v_lshl_add_u64 v[74:75], s[90:91], 0, v[16:17]
	v_add_co_u32_e32 v74, vcc, 0x15e00000, v74
	s_nop 1
	v_addc_co_u32_e32 v75, vcc, 0, v75, vcc
	v_lshl_add_u64 v[76:77], s[90:91], 0, v[18:19]
	v_lshl_add_u64 v[78:79], s[90:91], 0, v[14:15]
	v_add_co_u32_e32 v78, vcc, 0x1be00000, v78
	s_nop 1
	v_addc_co_u32_e32 v79, vcc, 0, v79, vcc
	v_lshl_add_u64 v[102:103], s[90:91], 0, v[12:13]
	s_cmpk_gt_i32 s34, 0x3fff
	s_cselect_b32 s23, 0x3fff, s26
	s_and_b32 s23, s23, s34
	v_lshl_or_b32 v20, s23, 6, v28
	s_mov_b64 exec, s[0:1]
	global_load_dwordx4 v[42:45], v[74:75], off
	s_mov_b64 exec, s[4:5]
	global_load_dwordx4 v[46:49], v[74:75], off offset:768
	s_mov_b64 exec, -1
	global_load_ushort v50, v[76:77], off
	global_load_dword v51, v20, s[84:85]
	global_load_dword v52, v20, s[96:97]
; __device__ __forceinline__ float bf_lo(unsigned w) { return __uint_as_float(w << 16); }
; __global__ void __launch_bounds__(512) fwd_megakernel(Args args) {
;     ...
;     if (PHMASK & 32) for (int m = gw; m < MTOK; m += NGW) {
;         const bf16_t* row = CQ + (size_t)m * 768;
;         {
;             u32x4 w = (u32x4){0u, 0u, 0u, 0u}; if (lane < 48) w = *(const u32x4*)(row + 8 * lane);
;             float v[8] = {bf_lo(w.x), bf_hi(w.x), bf_lo(w.y), bf_hi(w.y), bf_lo(w.z), bf_hi(w.z), bf_lo(w.w), bf_hi(w.w)}; float s = 0.f;
; #pragma unroll
;             for (int j = 0; j < 8; ++j) s += v[j] * v[j];
;             const float rr = __builtin_amdgcn_rsqf(wave_sum(s) * (1.0f / 384.0f) + EPS);
;             if (lane < 48) { const float* g = args.in[13] + 8 * lane; u32x4 o; o.x = pk2(v[0] * rr * g[0], v[1] * rr * g[1]); o.y = pk2(v[2] * rr * g[2], v[3] * rr * g[3]);
;                 o.z = pk2(v[4] * rr * g[4], v[5] * rr * g[5]); o.w = pk2(v[6] * rr * g[6], v[7] * rr * g[7]); *(u32x4*)(CQN + (size_t)m * 640 + 8 * lane) = o; }
;         }
;         {
;             u32x4 w = (u32x4){0u, 0u, 0u, 0u}; if (lane < 32) w = *(const u32x4*)(row + 384 + 8 * lane);
;             float v[8] = {bf_lo(w.x), bf_hi(w.x), bf_lo(w.y), bf_hi(w.y), bf_lo(w.z), bf_hi(w.z), bf_lo(w.w), bf_hi(w.w)}; float s = 0.f;
; #pragma unroll
;             for (int j = 0; j < 8; ++j) s += v[j] * v[j];
;             const float rr = __builtin_amdgcn_rsqf(wave_sum(s) * (1.0f / 256.0f) + EPS);
;             if (lane < 32) { const float* g = args.in[14] + 8 * lane; u32x4 o; o.x = pk2(v[0] * rr * g[0], v[1] * rr * g[1]); o.y = pk2(v[2] * rr * g[2], v[3] * rr * g[3]);
;                 o.z = pk2(v[4] * rr * g[4], v[5] * rr * g[5]); o.w = pk2(v[6] * rr * g[6], v[7] * rr * g[7]); *(u32x4*)(CQN + (size_t)m * 640 + 384 + 8 * lane) = o; }
;         }
;         {
;             const int i = lane & 31; const float v = __uint_as_float((unsigned)row[640 + i] << 16);
;             const float ssq = wave_sum(v * v) * 0.5f;
;             const float y = v * args.in[18][64 + i], pr = __shfl_xor(y, 16);
;             const int pos = tok_pos(m), fi = i & 15; const float c = ropeC_c[pos * 16 + fi], s = ropeC_s[pos * 16 + fi];
;             const float o = (i < 16) ? (y * c - pr * s) : (y * c + pr * s);
;             if (lane < 32) KPE[(size_t)m * 32 + i] = o;
;             if (lane == 0) SSKPE[m] = ssq;
;         }
.Lp9_loop:
	s_waitcnt vmcnt(0)
	v_lshlrev_b32_e32 v80, 16, v42
	v_and_b32_e32 v81, 0xffff0000, v42
	v_lshlrev_b32_e32 v82, 16, v43
	v_and_b32_e32 v83, 0xffff0000, v43
	v_lshlrev_b32_e32 v84, 16, v44
	v_and_b32_e32 v85, 0xffff0000, v44
	v_lshlrev_b32_e32 v86, 16, v45
	v_and_b32_e32 v87, 0xffff0000, v45
	v_lshlrev_b32_e32 v88, 16, v46
	v_and_b32_e32 v89, 0xffff0000, v46
	v_lshlrev_b32_e32 v90, 16, v47
	v_and_b32_e32 v91, 0xffff0000, v47
	v_lshlrev_b32_e32 v92, 16, v48
	v_and_b32_e32 v93, 0xffff0000, v48
	v_lshlrev_b32_e32 v94, 16, v49
	v_and_b32_e32 v95, 0xffff0000, v49
	v_lshlrev_b32_e32 v96, 16, v50
	v_mov_b32_e32 v111, v51
	v_mov_b32_e32 v112, v52
	v_lshl_add_u64 v[74:75], v[74:75], 0, s[20:21]
	v_lshl_add_u64 v[76:77], v[76:77], 0, s[20:21]
	s_add_i32 s22, s34, s30
	s_cmpk_gt_i32 s22, 0x3fff
	s_cselect_b32 s23, 0x3fff, s26
	s_and_b32 s23, s23, s22
	v_lshl_or_b32 v20, s23, 6, v28
	s_mov_b64 exec, s[0:1]
	global_load_dwordx4 v[42:45], v[74:75], off
	s_mov_b64 exec, s[4:5]
	global_load_dwordx4 v[46:49], v[74:75], off offset:768
	s_mov_b64 exec, -1
	global_load_ushort v50, v[76:77], off
	global_load_dword v51, v20, s[84:85]
	global_load_dword v52, v20, s[96:97]
	v_mul_f32_e32 v98, v80, v80
	v_fmac_f32_e32 v98, v81, v81
	v_fmac_f32_e32 v98, v82, v82
	v_fmac_f32_e32 v98, v83, v83
	v_fmac_f32_e32 v98, v84, v84
	v_fmac_f32_e32 v98, v85, v85
	v_fmac_f32_e32 v98, v86, v86
	v_fmac_f32_e32 v98, v87, v87
	v_mul_f32_e32 v99, v88, v88
	v_fmac_f32_e32 v99, v89, v89
	v_fmac_f32_e32 v99, v90, v90
	v_fmac_f32_e32 v99, v91, v91
	v_fmac_f32_e32 v99, v92, v92
	v_fmac_f32_e32 v99, v93, v93
	v_fmac_f32_e32 v99, v94, v94
	v_fmac_f32_e32 v99, v95, v95
	v_mul_f32_e32 v100, v96, v96
	v_mul_f32_e32 v97, v96, v72
	v_add_f32_dpp v104, v98, v98 quad_perm:[1,0,3,2] row_mask:0xf bank_mask:0xf
	v_add_f32_dpp v105, v99, v99 quad_perm:[1,0,3,2] row_mask:0xf bank_mask:0xf
	v_add_f32_dpp v106, v100, v100 quad_perm:[1,0,3,2] row_mask:0xf bank_mask:0xf
	v_add_f32_dpp v98, v104, v104 quad_perm:[2,3,0,1] row_mask:0xf bank_mask:0xf
	v_add_f32_dpp v99, v105, v105 quad_perm:[2,3,0,1] row_mask:0xf bank_mask:0xf
	v_add_f32_dpp v100, v106, v106 quad_perm:[2,3,0,1] row_mask:0xf bank_mask:0xf
	v_add_f32_dpp v104, v98, v98 row_half_mirror row_mask:0xf bank_mask:0xf
	v_add_f32_dpp v105, v99, v99 row_half_mirror row_mask:0xf bank_mask:0xf
	v_add_f32_dpp v106, v100, v100 row_half_mirror row_mask:0xf bank_mask:0xf
	v_add_f32_dpp v98, v104, v104 row_mirror row_mask:0xf bank_mask:0xf
	v_add_f32_dpp v99, v105, v105 row_mirror row_mask:0xf bank_mask:0xf
	v_add_f32_dpp v100, v106, v106 row_mirror row_mask:0xf bank_mask:0xf
	ds_bpermute_b32 v107, v129, v97
	ds_swizzle_b32 v104, v98 offset:swizzle(SWAP,16)
	ds_swizzle_b32 v105, v99 offset:swizzle(SWAP,16)
	ds_swizzle_b32 v106, v100 offset:swizzle(SWAP,16)
	s_waitcnt lgkmcnt(0)
	v_add_f32_e32 v98, v98, v104
	v_add_f32_e32 v99, v99, v105
	v_add_f32_e32 v100, v100, v106
	v_mov_b32_e32 v104, v98
	v_mov_b32_e32 v105, v99
	v_mov_b32_e32 v106, v100
	s_nop 1
	v_permlane32_swap_b32_e32 v98, v104
	v_permlane32_swap_b32_e32 v99, v105
	v_permlane32_swap_b32_e32 v100, v106
	v_add_f32_e32 v98, v98, v104
	v_add_f32_e32 v99, v99, v105
	v_add_f32_e32 v100, v100, v106
	v_fmamk_f32 v98, v98, 0x3b2aaaab, v4
	v_fmamk_f32 v99, v99, 0x3b800000, v4
	v_rsq_f32_e32 v98, v98
	v_rsq_f32_e32 v99, v99
	v_mul_f32_e32 v100, 0.5, v100
	v_mul_f32_e32 v107, v111, v107
	v_mul_f32_e32 v80, v80, v98
	v_mul_f32_e32 v81, v81, v98
	v_mul_f32_e32 v82, v82, v98
	v_mul_f32_e32 v83, v83, v98
	v_mul_f32_e32 v84, v84, v98
	v_mul_f32_e32 v85, v85, v98
	v_mul_f32_e32 v86, v86, v98
	v_mul_f32_e32 v87, v87, v98
	v_mul_f32_e32 v88, v88, v99
	v_mul_f32_e32 v89, v89, v99
	v_mul_f32_e32 v90, v90, v99
	v_mul_f32_e32 v91, v91, v99
	v_mul_f32_e32 v92, v92, v99
	v_mul_f32_e32 v93, v93, v99
	v_mul_f32_e32 v94, v94, v99
	v_mul_f32_e32 v95, v95, v99
	v_mul_f32_e32 v80, v80, v56
	v_mul_f32_e32 v81, v81, v57
	v_mul_f32_e32 v82, v82, v58
	v_mul_f32_e32 v83, v83, v59
	v_mul_f32_e32 v84, v84, v60
	v_mul_f32_e32 v85, v85, v61
	v_mul_f32_e32 v86, v86, v62
	v_mul_f32_e32 v87, v87, v63
	v_mul_f32_e32 v88, v88, v64
	v_mul_f32_e32 v89, v89, v65
	v_mul_f32_e32 v90, v90, v66
	v_mul_f32_e32 v91, v91, v67
	v_mul_f32_e32 v92, v92, v68
	v_mul_f32_e32 v93, v93, v69
	v_mul_f32_e32 v94, v94, v70
	v_mul_f32_e32 v95, v95, v71
	v_cndmask_b32_e64 v107, v107, -v107, s[6:7]
	v_fmac_f32_e32 v107, v97, v112
	v_cvt_pk_bf16_f32 v80, v80, v81
	v_cvt_pk_bf16_f32 v81, v82, v83
	v_cvt_pk_bf16_f32 v82, v84, v85
	v_cvt_pk_bf16_f32 v83, v86, v87
	v_cvt_pk_bf16_f32 v88, v88, v89
	v_cvt_pk_bf16_f32 v89, v90, v91
	v_cvt_pk_bf16_f32 v90, v92, v93
	v_cvt_pk_bf16_f32 v91, v94, v95
	s_mov_b64 exec, s[0:1]
	global_store_dwordx4 v[78:79], v[80:83], off
	s_mov_b64 exec, s[4:5]
	global_store_dwordx4 v[78:79], v[88:91], off offset:768
	global_store_dword v[102:103], v107, off
	s_mov_b64 exec, s[8:9]
	s_add_u32 s28, s90, s24
	s_addc_u32 s29, s91, s25
	global_store_dword v5, v100, s[28:29]
	s_mov_b64 exec, -1
	s_add_i32 s34, s34, s30
	s_add_u32 s24, s24, s14
	s_addc_u32 s25, s25, s15
	v_lshl_add_u64 v[78:79], v[78:79], 0, s[18:19]
	v_lshl_add_u64 v[102:103], v[102:103], 0, s[16:17]
	s_cmp_gt_i32 s34, 0xbfff
	s_cbranch_scc0 .Lp9_loop
